# SO11: chunk loop - fragments of the six state-update MFMAs prefetched right after the first MFMA into their own registers, MFMAs back to back (on SO7)
# speedup vs baseline: 1.0030x; 1.0030x over previous
.LBB0_441:
	v_add_u32_e32 v42, 0x22a00, v89
	ds_read_b128 v[34:37], v42
	ds_read_b128 v[38:41], v42 offset:32
	ds_read_b128 v[50:53], v42 offset:64
	ds_read_b128 v[54:57], v42 offset:96
	ds_read_b128 v[58:61], v42 offset:128
	ds_read_b128 v[62:65], v42 offset:160
	ds_read_b128 v[92:95], v42 offset:192
	ds_read_b128 v[96:99], v42 offset:224
	ds_read_b128 v[130:133], v82
	ds_read_b128 v[134:137], v88
	v_mov_b32_e32 v91, v82
	v_mov_b32_e32 v100, v90
	ds_read_b128 v[138:141], v87
	ds_read_b128 v[142:145], v86
	v_add_u32_e32 v46, 0x1a800, v90
	ds_read_b128 v[42:45], v85
	ds_read_b128 v[46:49], v46
	s_waitcnt lgkmcnt(13)
	v_pk_mul_f32 v[2:3], v[2:3], v[34:35]
	v_pk_mul_f32 v[4:5], v[4:5], v[36:37]
	s_waitcnt lgkmcnt(12)
	v_pk_mul_f32 v[6:7], v[6:7], v[38:39]
	s_waitcnt lgkmcnt(1)
	v_cndmask_b32_e64 v149, v45, 0, s[84:85]
	v_cndmask_b32_e64 v148, v44, 0, s[84:85]
	v_cndmask_b32_e64 v147, v43, 0, s[84:85]
	v_cndmask_b32_e64 v146, v42, 0, s[84:85]
	v_pk_mul_f32 v[8:9], v[8:9], v[40:41]
	v_pk_mul_f32 v[10:11], v[10:11], v[50:51]
	s_waitcnt lgkmcnt(0)
	v_mfma_f32_32x32x16_f16 v[34:49], v[46:49], v[146:149], 0
	v_add_u32_e32 v172, 0x14800, v82
	ds_read_b128 v[150:153], v172
	ds_read_b128 v[154:157], v172 offset:2048
	ds_read_b128 v[158:161], v172 offset:1024
	ds_read_b128 v[162:165], v172 offset:3072
	ds_read_b128 v[168:171], v84 offset:1024
	v_mul_f32_e64 v12, v12, v52
	v_mul_f32_e64 v13, v13, v53
	v_cvt_pk_f16_f32 v50, v2, v3
	v_cvt_pk_f16_f32 v51, v4, v5
	v_cvt_pk_f16_f32 v52, v6, v7
	v_cvt_pk_f16_f32 v53, v8, v9
	v_pk_mul_f32 v[14:15], v[14:15], v[54:55]
	v_pk_mul_f32 v[16:17], v[16:17], v[56:57]
	v_mfma_f32_32x32x16_f16 v[34:49], v[130:133], v[50:53], v[34:49]
	v_cvt_pk_f16_f32 v50, v10, v11
	v_cvt_pk_f16_f32 v51, v12, v13
	v_cvt_pk_f16_f32 v52, v14, v15
	v_cvt_pk_f16_f32 v53, v16, v17
	v_mul_f32_e64 v18, v18, v58
	v_mul_f32_e64 v19, v19, v59
	v_pk_mul_f32 v[20:21], v[20:21], v[60:61]
	v_pk_mul_f32 v[22:23], v[22:23], v[62:63]
	v_mfma_f32_32x32x16_f16 v[34:49], v[134:137], v[50:53], v[34:49]
	v_mul_f32_e64 v24, v24, v64
	v_mul_f32_e64 v25, v25, v65
	v_cvt_pk_f16_f32 v50, v18, v19
	v_cvt_pk_f16_f32 v51, v20, v21
	v_cvt_pk_f16_f32 v52, v22, v23
	v_cvt_pk_f16_f32 v53, v24, v25
	v_pk_mul_f32 v[26:27], v[26:27], v[92:93]
	v_pk_mul_f32 v[28:29], v[28:29], v[94:95]
	v_mfma_f32_32x32x16_f16 v[34:49], v[138:141], v[50:53], v[34:49]
	v_mul_f32_e64 v30, v30, v96
	v_mul_f32_e64 v31, v31, v97
	v_mul_f32_e64 v32, v32, v98
	v_mul_f32_e64 v33, v33, v99
	v_add_u32_e32 v100, 0x1b800, v100
	v_cvt_pk_f16_f32 v50, v26, v27
	v_cvt_pk_f16_f32 v51, v28, v29
	v_cvt_pk_f16_f32 v52, v30, v31
	v_cvt_pk_f16_f32 v53, v32, v33
	ds_read_b128 v[54:57], v100
	s_nop 0
	v_mfma_f32_32x32x16_f16 v[34:49], v[142:145], v[50:53], v[34:49]
	v_add_u32_e32 v97, 0, v84
	ds_read_b128 v[92:95], v97
	s_andn2_b64 vcc, exec, s[86:87]
	s_mov_b64 s[10:11], -1
	s_nop 7
	v_cvt_pk_f16_f32 v50, v34, v35
	v_cvt_pk_f16_f32 v51, v36, v37
	v_cvt_pk_f16_f32 v52, v38, v39
	v_cvt_pk_f16_f32 v53, v40, v41
	s_waitcnt lgkmcnt(1)
	s_nop 0
	v_mfma_f32_32x32x16_f16 v[50:65], v[54:57], v[50:53], 0
	s_nop 11
	v_cvt_pk_f16_f32 v50, v50, v51
	v_cvt_pk_f16_f32 v51, v52, v53
	v_cvt_pk_f16_f32 v52, v54, v55
	v_cvt_pk_f16_f32 v53, v56, v57
	s_waitcnt lgkmcnt(0)
	s_nop 0
	v_mfma_f32_32x32x16_f16 v[2:17], v[150:153], v[50:53], v[2:17]
	v_mfma_f32_32x32x16_f16 v[18:33], v[154:157], v[50:53], v[18:33]
	v_mfma_f32_32x32x16_f16 v[34:49], v[92:95], v[50:53], v[34:49]
	v_mfma_f32_32x32x16_f16 v[2:17], v[158:161], v[146:149], v[2:17]
	v_mfma_f32_32x32x16_f16 v[18:33], v[162:165], v[146:149], v[18:33]
	v_mfma_f32_32x32x16_f16 v[34:49], v[168:171], v[146:149], v[34:49]
	s_cbranch_vccnz .LBB0_443
	s_nop 10
	v_add_u32_e32 v35, 0x20000, v83
	v_cvt_pk_bf16_f32 v34, v42, v43
	v_cvt_pk_bf16_f32 v36, v44, v45
	v_cvt_pk_bf16_f32 v37, v46, v47
	v_cvt_pk_bf16_f32 v38, v48, v49
	ds_write_b16 v35, v34
	ds_write_b16_d16_hi v35, v34 offset:128
	ds_write_b16 v35, v36 offset:256
	ds_write_b16_d16_hi v35, v36 offset:384
	ds_write_b16 v35, v37 offset:1024
	ds_write_b16_d16_hi v35, v37 offset:1152
	ds_write_b16 v35, v38 offset:1280
	ds_write_b16_d16_hi v35, v38 offset:1408
	s_mov_b64 s[10:11], 0
